# deferred weight conversion (grid-size generic: grids other than 256 keep everything in phase 0), 768 items per barrier = waves 1-3 of every workgroup
# speedup vs baseline: 1.0117x; 1.0117x over previous
; __device__ __forceinline__ void prologue(const Args& a, LAS unsigned char* lds, int vcu, int G, int wave, int lane, int tid) {
;     ...
;     const int gw = vcu * NWAVES + wave, NGW = G * NWAVES;
;     constexpr int I_QKV = 16 * 48, I_SQ = 16 * 16, I_POOL = 4 * 4, I_UP = 16 * 64, I_DN = 64 * 16;
;     constexpr int NITEMS = 2 * I_QKV + 2 * I_SQ + 4 * I_POOL + I_QKV + I_SQ + 4 * I_UP + 4 * I_DN;
;     const float* nmix = a.in[2]; const float* nmlp = a.in[3];
;     for (int it = gw; it < NITEMS; it += NGW) {
;         int r = it;
.LBB0_525:
	s_add_i32 s0, s70, s85
	s_lshl_b32 s12, s65, 3
	s_waitcnt vmcnt(0)
	v_and_b32_e32 v2, 63, v221
	s_movk_i32 s2, 0x2ff
	s_cmp_lg_u32 s65, 0x100
	s_cselect_b32 s2, 0x2c3f, s2
	s_cmp_gt_i32 s0, s2
	v_lshlrev_b32_e32 v66, 2, v2
	v_lshlrev_b32_e32 v68, 3, v2
	s_cbranch_scc1 .LBB0_564

; __device__ __forceinline__ void prologue(const Args& a, LAS unsigned char* lds, int vcu, int G, int wave, int lane, int tid) {
;     ...
;     for (int it = gw; it < NITEMS; it += NGW) {
;         int r = it;
.LBB0_528:
	s_cmp_lg_u32 s32, 0
	s_cbranch_scc1 .Lmy_p0_ret
	s_add_i32 s7, s7, s12
	s_add_i32 s1, s1, s6
	s_add_i32 s13, s13, s14
	s_add_i32 s15, s15, s16
	s_add_i32 s2, s7, 0x1c40
	s_add_i32 s17, s17, s18
	s_movk_i32 s84, 0x2ff
	s_cmp_lg_u32 s65, 0x100
	s_cselect_b32 s84, 0x2c3f, s84
	s_cmp_gt_i32 s2, s84
	s_cbranch_scc1 .LBB0_564

; __device__ __forceinline__ void prologue(const Args& a, LAS unsigned char* lds, int vcu, int G, int wave, int lane, int tid) {
;     ...
;     const int gw = vcu * NWAVES + wave, NGW = G * NWAVES;
;     constexpr int I_QKV = 16 * 48, I_SQ = 16 * 16, I_POOL = 4 * 4, I_UP = 16 * 64, I_DN = 64 * 16;
;     constexpr int NITEMS = 2 * I_QKV + 2 * I_SQ + 4 * I_POOL + I_QKV + I_SQ + 4 * I_UP + 4 * I_DN;
;     const float* nmix = a.in[2]; const float* nmlp = a.in[3];
;     for (int it = gw; it < NITEMS; it += NGW) {
;         int r = it;
.Lmy_items:
	s_mov_b64 exec, -1
	v_readlane_b32 s65, v253, 2
	s_cmp_lg_u32 s65, 0x100
	s_cbranch_scc1 .LBB0_633
	v_readfirstlane_b32 s3, v0
	s_lshr_b32 s3, s3, 6
	s_cmp_gt_u32 s3, 3
	s_cbranch_scc1 .LBB0_633
	v_writelane_b32 v200, s0, 0
	v_writelane_b32 v200, s1, 1
	v_writelane_b32 v200, s2, 2
	v_writelane_b32 v200, s3, 3
	v_writelane_b32 v200, s4, 4
	v_writelane_b32 v200, s5, 5
	v_writelane_b32 v200, s6, 6
	v_writelane_b32 v200, s7, 7
	v_writelane_b32 v200, s8, 8
	v_writelane_b32 v200, s9, 9
	v_writelane_b32 v200, s10, 10
	v_writelane_b32 v200, s11, 11
	v_writelane_b32 v200, s12, 12
	v_writelane_b32 v200, s13, 13
	v_writelane_b32 v200, s14, 14
	v_writelane_b32 v200, s15, 15
	v_writelane_b32 v200, s16, 16
	v_writelane_b32 v200, s17, 17
	v_writelane_b32 v200, s18, 18
	v_writelane_b32 v200, s19, 19
	v_writelane_b32 v200, s68, 20
	v_writelane_b32 v200, s69, 21
	v_writelane_b32 v200, s70, 22
	v_writelane_b32 v200, s71, 23
	v_writelane_b32 v200, s72, 24
	v_writelane_b32 v200, s73, 25
	v_writelane_b32 v200, s74, 26
	v_writelane_b32 v200, s75, 27
	v_writelane_b32 v200, s76, 28
	v_writelane_b32 v200, s77, 29
	v_writelane_b32 v200, s78, 30
	v_writelane_b32 v200, s79, 31
	v_writelane_b32 v200, s80, 32
	v_writelane_b32 v200, s81, 33
	v_writelane_b32 v200, s82, 34
	v_writelane_b32 v200, s83, 35
	v_writelane_b32 v200, s86, 36
	s_add_i32 s2, s66, -1
	s_add_i32 s4, s66, -2
	s_cmp_gt_u32 s66, 8
	s_cselect_b32 s2, s4, s2
	s_add_i32 s5, s3, -1
	s_lshl_b32 s5, s5, 8
	v_readlane_b32 s6, v255, 47
	s_lshr_b32 s7, s6, 3
	s_add_i32 s5, s5, s7
	s_cmp_ge_u32 s5, 768
	s_cbranch_scc1 .Lmy_items_restore
	s_mul_i32 s2, s2, 768
	s_add_i32 s2, s2, s5
	s_cmp_ge_u32 s2, 10560
	s_cbranch_scc1 .Lmy_items_restore
	s_mov_b32 s4, 1536
	s_cmp_ge_u32 s2, 256
	s_cselect_b32 s4, 2880, s4
	s_cmp_ge_u32 s2, 1280
	s_cselect_b32 s4, 5952, s4
	s_cmp_ge_u32 s2, 2304
	s_cselect_b32 s4, -256, s4
	s_cmp_ge_u32 s2, 2368
	s_cselect_b32 s4, 1792, s4
	s_cmp_ge_u32 s2, 3392
	s_cselect_b32 s4, 4864, s4
	s_cmp_ge_u32 s2, 4416
	s_cselect_b32 s4, -2304, s4
	s_cmp_ge_u32 s2, 5184
	s_cselect_b32 s4, -2304, s4
	s_cmp_ge_u32 s2, 5440
	s_cselect_b32 s4, -256, s4
	s_cmp_ge_u32 s2, 6464
	s_cselect_b32 s4, 2816, s4
	s_cmp_ge_u32 s2, 7488
	s_cselect_b32 s4, -6720, s4
	s_cmp_ge_u32 s2, 8256
	s_cselect_b32 s4, -6464, s4
	s_cmp_ge_u32 s2, 8512
	s_cselect_b32 s4, -2304, s4
	s_cmp_ge_u32 s2, 9536
	s_cselect_b32 s4, 768, s4
	s_add_i32 s19, s2, s4
	v_mov_b32_e32 v221, v0
	v_readlane_b32 s65, v253, 2
	s_mov_b32 s70, s3
	s_mov_b32 s85, s6
	v_readlane_b32 s28, v255, 48
	s_add_i32 s0, s70, s85
	s_sub_i32 s19, s19, s0
	s_lshl_b32 s12, s65, 3
	v_and_b32_e32 v2, 63, v221
	v_lshlrev_b32_e32 v66, 2, v2
	v_lshlrev_b32_e32 v68, 3, v2
	s_mov_b32 s32, 1
	s_branch .Lmy_p0_init
